# adds counted vmcnt in the attention K/V prefetch (3-deep prefetch kept in flight; compiler's full drains removed)
# speedup vs baseline: 1.0065x; 1.0052x over previous
;     ...
;             if (t + 3 < nkt) AT_LOAD(ka0, ka1, va0, va1, bra, t + 3);
.LBB0_393:
	s_add_i32 s45, s43, -2
	s_cmp_lt_i32 s45, s40
	s_cselect_b64 s[8:9], -1, 0
	s_cmp_ge_i32 s45, s40
	s_cbranch_scc1 .LBB0_397
	v_add_u32_e32 v50, s41, v235
	v_add_u32_e32 v48, 0xc0, v50
	v_add_u32_e32 v50, 0xe0, v50
	v_ashrrev_i32_e32 v49, 31, v48
	v_ashrrev_i32_e32 v51, 31, v50
	v_lshlrev_b64 v[56:57], 14, v[48:49]
	v_lshlrev_b64 v[58:59], 14, v[50:51]
	v_lshl_add_u64 v[48:49], v[214:215], 0, v[56:57]
	v_lshl_add_u64 v[52:53], v[214:215], 0, v[58:59]
	v_lshl_add_u64 v[56:57], v[216:217], 0, v[56:57]
	v_lshl_add_u64 v[60:61], v[216:217], 0, v[58:59]
	global_load_dwordx4 v[48:51], v[48:49], off
	s_nop 0
	global_load_dwordx4 v[52:55], v[52:53], off
	s_nop 0
	global_load_dwordx4 v[56:59], v[56:57], off
	s_nop 0
	global_load_dwordx4 v[60:63], v[60:61], off
	s_and_saveexec_b64 s[12:13], s[38:39]
	s_cbranch_execz .LBB0_396
	v_add_u32_e32 v100, s41, v212
	v_add_u32_e32 v100, 0xc0, v100
	v_ashrrev_i32_e32 v101, 31, v100
	v_lshl_add_u64 v[100:101], v[100:101], 2, s[2:3]
	global_load_dword v223, v[100:101], off

;     ...
;             if (t + 3 < nkt) AT_LOAD(ka0, ka1, va0, va1, bra, t + 3);
;             attn_tile(lds, t & 1, t * 64, qmin, qi, ci, lane, qf, o, m, lsum);
;             if (t + 1 < nkt) AT_STORE(kb0, kb1, vb0, vb1, brb, t + 1);
.LBB0_401:
	s_add_i32 s48, s43, -4
	s_cmp_lt_i32 s48, s40
	s_cselect_b64 s[12:13], -1, 0
	s_cmp_ge_i32 s48, s40
	s_cbranch_scc1 .LBB0_405
	s_and_b32 s49, s48, 1
	s_mul_i32 s14, s49, 0x4400
	v_add_u32_e32 v100, s14, v241
	s_add_i32 s14, s43, -2
	s_cmp_lt_i32 s14, s40
	s_cbranch_scc1 .Latw_1_8
	s_add_i32 s14, s43, -3
	s_cmp_lt_i32 s14, s40
	s_cbranch_scc1 .Latw_1_4
	s_waitcnt vmcnt(0)
	s_branch .Latw_1_d
.Latw_1_8:
	s_waitcnt vmcnt(8)
	s_branch .Latw_1_d

.Latw_1_d:
	ds_write_b128 v100, v[8:11]
	ds_write_b128 v100, v[12:15] offset:8704
	ds_write_b128 v100, v[24:27] offset:34816
	ds_write_b128 v100, v[28:31] offset:43520
	s_and_saveexec_b64 s[14:15], s[38:39]
	s_cbranch_execz .LBB0_404
	v_mov_b32_e32 v100, s44
	ds_read_b32 v100, v100
	v_lshl_add_u32 v101, s49, 8, v240
	s_waitcnt lgkmcnt(0)
	v_add_f32_e32 v100, v242, v100
	v_mul_f32_e32 v100, 0x3fb8aa3b, v100
	ds_write_b32 v101, v100

;     ...
;             if (t + 3 < nkt) AT_LOAD(kb0, kb1, vb0, vb1, brb, t + 3);
.LBB0_405:
	s_andn2_b64 vcc, exec, s[12:13]
	s_mov_b64 s[12:13], -1
	s_waitcnt lgkmcnt(0)
	s_barrier
	s_cbranch_vccnz .LBB0_411
	s_add_i32 s12, s43, -1
	s_cmp_ge_i32 s12, s40
	s_cbranch_scc1 .LBB0_412
	v_add_u32_e32 v10, s41, v235
	v_add_u32_e32 v8, 0x100, v10
	v_add_u32_e32 v10, 0x120, v10
	v_ashrrev_i32_e32 v9, 31, v8
	v_ashrrev_i32_e32 v11, 31, v10
	v_lshlrev_b64 v[24:25], 14, v[8:9]
	v_lshlrev_b64 v[26:27], 14, v[10:11]
	v_lshl_add_u64 v[8:9], v[214:215], 0, v[24:25]
	v_lshl_add_u64 v[12:13], v[214:215], 0, v[26:27]
	v_lshl_add_u64 v[24:25], v[216:217], 0, v[24:25]
	v_lshl_add_u64 v[28:29], v[216:217], 0, v[26:27]
	global_load_dwordx4 v[8:11], v[8:9], off
	s_nop 0
	global_load_dwordx4 v[12:15], v[12:13], off
	s_nop 0
	global_load_dwordx4 v[24:27], v[24:25], off
	s_nop 0
	global_load_dwordx4 v[28:31], v[28:29], off
	s_and_saveexec_b64 s[12:13], s[38:39]
	s_cbranch_execz .LBB0_409
	v_add_u32_e32 v100, s41, v212
	v_add_u32_e32 v100, 0x100, v100
	v_ashrrev_i32_e32 v101, 31, v100
	v_lshl_add_u64 v[100:101], v[100:101], 2, s[2:3]
	global_load_dword v242, v[100:101], off

;     ...
;             if (t + 1 < nkt) AT_STORE(kc0, kc1, vc0, vc1, brc, t + 1);
.LBB0_416:
	s_mul_i32 s14, s46, 0x4400
	v_add_u32_e32 v100, s14, v241
	s_add_i32 s14, s43, -1
	s_cmp_lt_i32 s14, s40
	s_cbranch_scc1 .Latw_2_8
	s_add_i32 s14, s43, -2
	s_cmp_lt_i32 s14, s40
	s_cbranch_scc1 .Latw_2_4
	s_waitcnt vmcnt(0)
	s_branch .Latw_2_d

.Latw_2_d:
	ds_write_b128 v100, v[0:3]
	ds_write_b128 v100, v[4:7] offset:8704
	ds_write_b128 v100, v[16:19] offset:34816
	ds_write_b128 v100, v[20:23] offset:43520
	s_and_saveexec_b64 s[14:15], s[38:39]
	s_cbranch_execz .LBB0_418
	v_mov_b32_e32 v100, s44
	ds_read_b32 v100, v100 offset:4
	v_lshl_add_u32 v101, s46, 8, v240
	s_waitcnt lgkmcnt(0)
	v_add_f32_e32 v100, v243, v100
	v_mul_f32_e32 v100, 0x3fb8aa3b, v100
	ds_write_b32 v101, v100

;     ...
;             if (t + 3 < nkt) AT_LOAD(kc0, kc1, vc0, vc1, brc, t + 3);
.LBB0_419:
	s_andn2_b64 vcc, exec, s[12:13]
	s_mov_b64 s[12:13], -1
	s_waitcnt lgkmcnt(0)
	s_barrier
	s_cbranch_vccnz .LBB0_425
	s_cmp_ge_i32 s43, s40
	s_cbranch_scc1 .LBB0_426
	v_add_u32_e32 v2, s41, v235
	v_add_u32_e32 v0, 0x140, v2
	v_add_u32_e32 v2, 0x160, v2
	v_ashrrev_i32_e32 v1, 31, v0
	v_ashrrev_i32_e32 v3, 31, v2
	v_lshlrev_b64 v[16:17], 14, v[0:1]
	v_lshlrev_b64 v[18:19], 14, v[2:3]
	v_lshl_add_u64 v[0:1], v[214:215], 0, v[16:17]
	v_lshl_add_u64 v[4:5], v[214:215], 0, v[18:19]
	v_lshl_add_u64 v[16:17], v[216:217], 0, v[16:17]
	v_lshl_add_u64 v[20:21], v[216:217], 0, v[18:19]
	global_load_dwordx4 v[0:3], v[0:1], off
	s_nop 0
	global_load_dwordx4 v[4:7], v[4:5], off
	s_nop 0
	global_load_dwordx4 v[16:19], v[16:17], off
	s_nop 0
	global_load_dwordx4 v[20:23], v[20:21], off
	s_and_saveexec_b64 s[12:13], s[38:39]
	s_cbranch_execz .LBB0_423
	v_add_u32_e32 v100, s41, v212
	v_add_u32_e32 v100, 0x140, v100
	v_ashrrev_i32_e32 v101, 31, v100
	v_lshl_add_u64 v[100:101], v[100:101], 2, s[2:3]
	global_load_dword v243, v[100:101], off

;     ...
;             if (t + 1 < nkt) AT_STORE(ka0, ka1, va0, va1, bra, t + 1);
.LBB0_430:
	s_and_b32 s12, s45, 1
	s_mul_i32 s8, s12, 0x4400
	v_add_u32_e32 v100, s8, v241
	s_add_i32 s8, s43, 0
	s_cmp_lt_i32 s8, s40
	s_cbranch_scc1 .Latw_3_8
	s_add_i32 s8, s43, -1
	s_cmp_lt_i32 s8, s40
	s_cbranch_scc1 .Latw_3_4
	s_waitcnt vmcnt(0)
	s_branch .Latw_3_d

.Latw_3_d:
	ds_write_b128 v100, v[48:51]
	ds_write_b128 v100, v[52:55] offset:8704
	ds_write_b128 v100, v[56:59] offset:34816
	ds_write_b128 v100, v[60:63] offset:43520
	s_and_saveexec_b64 s[8:9], s[38:39]
	s_cbranch_execz .LBB0_391
	v_mov_b32_e32 v100, s44
	ds_read_b32 v100, v100 offset:8
	v_lshl_add_u32 v101, s12, 8, v240
	s_waitcnt lgkmcnt(0)
	v_add_f32_e32 v100, v223, v100
	v_mul_f32_e32 v100, 0x3fb8aa3b, v100
	ds_write_b32 v101, v100
	s_branch .LBB0_391
